# phase E: hand-written branch epilogue (loads up front, MFMA-layout dwordx2) + first 4 gate groups in spare LDS
# speedup vs baseline: 1.0003x; 1.0003x over previous
; __device__ __forceinline__ float bflo(unsigned u) { return __uint_as_float(u << 16); }
; __device__ __forceinline__ float bfhi(unsigned u) { return __uint_as_float(u & 0xFFFF0000u); }
; __device__ __forceinline__ void phaseE(const Params& p, int layer) {
;     ...
;               uint4 g4[2]; uint2 old[2][2];
; #pragma unroll
;               for (int mm = 0; mm < 2; mm++) {
;                 const int m = mh * 2 + mm;
;                 g4[mm] = *(const uint4*)(gsb + ((ai * 2 + bj) * 4 + m) * 8192 + gs_lane);
;                 if (br) {
; #pragma unroll
;                   for (int n = 0; n < 2; n++)
;                     old[mm][n] = *(const uint2*)(mb + ((size_t)(ai * 128 + m * 16) * 2048 + bj * 128 + n * 16) * 2 + lane_m);
;                 }
;               }
; #pragma unroll
;               for (int mm = 0; mm < 2; mm++) {
;                 const int m = mh * 2 + mm;
;                 const unsigned gq[4] = {g4[mm].x, g4[mm].y, g4[mm].z, g4[mm].w};
; #pragma unroll
;                 for (int n = 0; n < 2; n++) {
;                   f32x4 v = acc[ai][bj][m][n];
;                   float o0 = bflo(gq[2 * n]) * v[0], o1 = bfhi(gq[2 * n]) * v[1], o2 = bflo(gq[2 * n + 1]) * v[2], o3 = bfhi(gq[2 * n + 1]) * v[3];
;                   char* mp = mb + ((size_t)(ai * 128 + m * 16) * 2048 + bj * 128 + n * 16) * 2 + lane_m;
;                   if (br) { o0 += bflo(old[mm][n].x); o1 += bfhi(old[mm][n].x); o2 += bflo(old[mm][n].y); o3 += bfhi(old[mm][n].y); }
;                   *(uint2*)mp = make_uint2(pk2(o0, o1), pk2(o2, o3));
;                 }
;               }
.LBB0_2323:
	v_readlane_b32 s0, v253, 51
	v_readlane_b32 s1, v253, 52
	v_add_u32_e32 v165, 0x20000, v160
	v_mov_b32_e32 v163, v162
	s_cmp_lg_u64 s[12:13], 0
	s_nop 3
	s_cbranch_scc0 .Lbrepi_first
	ds_read_b128 v[128:131], v165
	global_load_dwordx2 v[132:133], v163, s[6:7] offset:0
	global_load_dwordx2 v[134:135], v163, s[6:7] offset:32
	ds_read_b128 v[136:139], v165 offset:8192
	v_add_u32_e32 v210, 0x10000, v163
	global_load_dwordx2 v[140:141], v210, s[6:7] offset:0
	global_load_dwordx2 v[142:143], v210, s[6:7] offset:32
	ds_read_b128 v[148:151], v165 offset:16384
	v_add_u32_e32 v211, 0x20000, v163
	global_load_dwordx2 v[152:153], v211, s[6:7] offset:0
	global_load_dwordx2 v[154:155], v211, s[6:7] offset:32
	ds_read_b128 v[164:167], v165 offset:24576
	v_add_u32_e32 v210, 0x30000, v163
	global_load_dwordx2 v[168:169], v210, s[6:7] offset:0
	global_load_dwordx2 v[170:171], v210, s[6:7] offset:32
	v_add_u32_e32 v146, 0x8000, v160
	global_load_dwordx4 v[172:175], v146, s[0:1]
	global_load_dwordx2 v[176:177], v163, s[6:7] offset:256
	global_load_dwordx2 v[178:179], v163, s[6:7] offset:288
	v_add_u32_e32 v147, 0xa000, v160
	global_load_dwordx4 v[180:183], v147, s[0:1]
	v_add_u32_e32 v211, 0x10000, v163
	global_load_dwordx2 v[184:185], v211, s[6:7] offset:256
	global_load_dwordx2 v[186:187], v211, s[6:7] offset:288
	v_add_u32_e32 v146, 0xc000, v160
	global_load_dwordx4 v[188:191], v146, s[0:1]
	v_add_u32_e32 v210, 0x20000, v163
	global_load_dwordx2 v[192:193], v210, s[6:7] offset:256
	global_load_dwordx2 v[194:195], v210, s[6:7] offset:288
	v_add_u32_e32 v147, 0xe000, v160
	global_load_dwordx4 v[212:215], v147, s[0:1]
	v_add_u32_e32 v211, 0x30000, v163
	global_load_dwordx2 v[216:217], v211, s[6:7] offset:256
	global_load_dwordx2 v[218:219], v211, s[6:7] offset:288
	v_add_u32_e32 v146, 0x10000, v160
	global_load_dwordx4 v[220:223], v146, s[0:1]
	v_add_u32_e32 v210, 0x80000, v163
	global_load_dwordx2 v[224:225], v210, s[6:7] offset:0
	global_load_dwordx2 v[226:227], v210, s[6:7] offset:32
	v_add_u32_e32 v147, 0x12000, v160
	global_load_dwordx4 v[228:231], v147, s[0:1]
	v_add_u32_e32 v211, 0x90000, v163
	global_load_dwordx2 v[232:233], v211, s[6:7] offset:0
	global_load_dwordx2 v[234:235], v211, s[6:7] offset:32
	v_add_u32_e32 v146, 0x14000, v160
	global_load_dwordx4 v[236:239], v146, s[0:1]
	v_add_u32_e32 v210, 0xa0000, v163
	global_load_dwordx2 v[240:241], v210, s[6:7] offset:0
	global_load_dwordx2 v[242:243], v210, s[6:7] offset:32
	s_waitcnt vmcnt(27) lgkmcnt(0)
	v_lshlrev_b32_e32 v156, 16, v128
	v_and_b32_e32 v157, 0xffff0000, v128
	v_lshlrev_b32_e32 v158, 16, v129
	v_and_b32_e32 v159, 0xffff0000, v129
	v_pk_mul_f32 v[156:157], v[124:125], v[156:157]
	v_pk_mul_f32 v[158:159], v[126:127], v[158:159]
	v_lshlrev_b32_e32 v244, 16, v130
	v_and_b32_e32 v245, 0xffff0000, v130
	v_lshlrev_b32_e32 v246, 16, v131
	v_and_b32_e32 v247, 0xffff0000, v131
	v_pk_mul_f32 v[244:245], v[120:121], v[244:245]
	v_pk_mul_f32 v[246:247], v[122:123], v[246:247]
	v_lshlrev_b32_e32 v196, 16, v132
	v_and_b32_e32 v197, 0xffff0000, v132
	v_lshlrev_b32_e32 v198, 16, v133
	v_and_b32_e32 v199, 0xffff0000, v133
	v_pk_add_f32 v[156:157], v[156:157], v[196:197]
	v_pk_add_f32 v[158:159], v[158:159], v[198:199]
	v_lshlrev_b32_e32 v200, 16, v134
	v_and_b32_e32 v201, 0xffff0000, v134
	v_lshlrev_b32_e32 v204, 16, v135
	v_and_b32_e32 v205, 0xffff0000, v135
	v_pk_add_f32 v[244:245], v[244:245], v[200:201]
	v_pk_add_f32 v[246:247], v[246:247], v[204:205]
	v_cvt_pk_bf16_f32 v156, v156, v157
	v_cvt_pk_bf16_f32 v157, v158, v159
	v_cvt_pk_bf16_f32 v158, v244, v245
	v_cvt_pk_bf16_f32 v159, v246, v247
	global_store_dwordx2 v163, v[156:157], s[6:7] offset:0
	global_store_dwordx2 v163, v[158:159], s[6:7] offset:32
	v_add_u32_e32 v147, 0x16000, v160
	global_load_dwordx4 v[128:131], v147, s[0:1]
	v_add_u32_e32 v211, 0xb0000, v163
	global_load_dwordx2 v[132:133], v211, s[6:7] offset:0
	global_load_dwordx2 v[134:135], v211, s[6:7] offset:32
	s_waitcnt vmcnt(30) lgkmcnt(0)
	v_lshlrev_b32_e32 v156, 16, v136
	v_and_b32_e32 v157, 0xffff0000, v136
	v_lshlrev_b32_e32 v158, 16, v137
	v_and_b32_e32 v159, 0xffff0000, v137
	v_pk_mul_f32 v[156:157], v[116:117], v[156:157]
	v_pk_mul_f32 v[158:159], v[118:119], v[158:159]
	v_lshlrev_b32_e32 v244, 16, v138
	v_and_b32_e32 v245, 0xffff0000, v138
	v_lshlrev_b32_e32 v246, 16, v139
	v_and_b32_e32 v247, 0xffff0000, v139
	v_pk_mul_f32 v[244:245], v[112:113], v[244:245]
	v_pk_mul_f32 v[246:247], v[114:115], v[246:247]
	v_lshlrev_b32_e32 v196, 16, v140
	v_and_b32_e32 v197, 0xffff0000, v140
	v_lshlrev_b32_e32 v198, 16, v141
	v_and_b32_e32 v199, 0xffff0000, v141
	v_pk_add_f32 v[156:157], v[156:157], v[196:197]
	v_pk_add_f32 v[158:159], v[158:159], v[198:199]
	v_lshlrev_b32_e32 v200, 16, v142
	v_and_b32_e32 v201, 0xffff0000, v142
	v_lshlrev_b32_e32 v204, 16, v143
	v_and_b32_e32 v205, 0xffff0000, v143
	v_pk_add_f32 v[244:245], v[244:245], v[200:201]
	v_pk_add_f32 v[246:247], v[246:247], v[204:205]
	v_cvt_pk_bf16_f32 v156, v156, v157
	v_cvt_pk_bf16_f32 v157, v158, v159
	v_cvt_pk_bf16_f32 v158, v244, v245
	v_cvt_pk_bf16_f32 v159, v246, v247
	v_add_u32_e32 v210, 0x10000, v163
	global_store_dwordx2 v210, v[156:157], s[6:7] offset:0
	global_store_dwordx2 v210, v[158:159], s[6:7] offset:32
	v_add_u32_e32 v146, 0x18000, v160
	global_load_dwordx4 v[136:139], v146, s[0:1]
	v_add_u32_e32 v211, 0x80000, v163
	global_load_dwordx2 v[140:141], v211, s[6:7] offset:256
	global_load_dwordx2 v[142:143], v211, s[6:7] offset:288
	s_waitcnt vmcnt(33) lgkmcnt(0)
; __device__ __forceinline__ float bflo(unsigned u) { return __uint_as_float(u << 16); }
; __device__ __forceinline__ float bfhi(unsigned u) { return __uint_as_float(u & 0xFFFF0000u); }
; __device__ __forceinline__ void phaseE(const Params& p, int layer) {
;     ...
;               uint4 g4[2]; uint2 old[2][2];
; #pragma unroll
;               for (int mm = 0; mm < 2; mm++) {
;                 const int m = mh * 2 + mm;
;                 g4[mm] = *(const uint4*)(gsb + ((ai * 2 + bj) * 4 + m) * 8192 + gs_lane);
;                 if (br) {
; #pragma unroll
;                   for (int n = 0; n < 2; n++)
;                     old[mm][n] = *(const uint2*)(mb + ((size_t)(ai * 128 + m * 16) * 2048 + bj * 128 + n * 16) * 2 + lane_m);
;                 }
;               }
; #pragma unroll
;               for (int mm = 0; mm < 2; mm++) {
;                 const int m = mh * 2 + mm;
;                 const unsigned gq[4] = {g4[mm].x, g4[mm].y, g4[mm].z, g4[mm].w};
; #pragma unroll
;                 for (int n = 0; n < 2; n++) {
;                   f32x4 v = acc[ai][bj][m][n];
;                   float o0 = bflo(gq[2 * n]) * v[0], o1 = bfhi(gq[2 * n]) * v[1], o2 = bflo(gq[2 * n + 1]) * v[2], o3 = bfhi(gq[2 * n + 1]) * v[3];
;                   char* mp = mb + ((size_t)(ai * 128 + m * 16) * 2048 + bj * 128 + n * 16) * 2 + lane_m;
;                   if (br) { o0 += bflo(old[mm][n].x); o1 += bfhi(old[mm][n].x); o2 += bflo(old[mm][n].y); o3 += bfhi(old[mm][n].y); }
;                   *(uint2*)mp = make_uint2(pk2(o0, o1), pk2(o2, o3));
;                 }
;               }
	v_lshlrev_b32_e32 v156, 16, v148
	v_and_b32_e32 v157, 0xffff0000, v148
	v_lshlrev_b32_e32 v158, 16, v149
	v_and_b32_e32 v159, 0xffff0000, v149
	v_pk_mul_f32 v[156:157], v[108:109], v[156:157]
	v_pk_mul_f32 v[158:159], v[110:111], v[158:159]
	v_lshlrev_b32_e32 v244, 16, v150
	v_and_b32_e32 v245, 0xffff0000, v150
	v_lshlrev_b32_e32 v246, 16, v151
	v_and_b32_e32 v247, 0xffff0000, v151
	v_pk_mul_f32 v[244:245], v[104:105], v[244:245]
	v_pk_mul_f32 v[246:247], v[106:107], v[246:247]
	v_lshlrev_b32_e32 v196, 16, v152
	v_and_b32_e32 v197, 0xffff0000, v152
	v_lshlrev_b32_e32 v198, 16, v153
	v_and_b32_e32 v199, 0xffff0000, v153
	v_pk_add_f32 v[156:157], v[156:157], v[196:197]
	v_pk_add_f32 v[158:159], v[158:159], v[198:199]
	v_lshlrev_b32_e32 v200, 16, v154
	v_and_b32_e32 v201, 0xffff0000, v154
	v_lshlrev_b32_e32 v204, 16, v155
	v_and_b32_e32 v205, 0xffff0000, v155
	v_pk_add_f32 v[244:245], v[244:245], v[200:201]
	v_pk_add_f32 v[246:247], v[246:247], v[204:205]
	v_cvt_pk_bf16_f32 v156, v156, v157
	v_cvt_pk_bf16_f32 v157, v158, v159
	v_cvt_pk_bf16_f32 v158, v244, v245
	v_cvt_pk_bf16_f32 v159, v246, v247
	v_add_u32_e32 v210, 0x20000, v163
	global_store_dwordx2 v210, v[156:157], s[6:7] offset:0
	global_store_dwordx2 v210, v[158:159], s[6:7] offset:32
	v_add_u32_e32 v147, 0x1a000, v160
	global_load_dwordx4 v[148:151], v147, s[0:1]
	v_add_u32_e32 v211, 0x90000, v163
	global_load_dwordx2 v[152:153], v211, s[6:7] offset:256
	global_load_dwordx2 v[154:155], v211, s[6:7] offset:288
	s_waitcnt vmcnt(36) lgkmcnt(0)
	v_lshlrev_b32_e32 v156, 16, v164
	v_and_b32_e32 v157, 0xffff0000, v164
	v_lshlrev_b32_e32 v158, 16, v165
	v_and_b32_e32 v159, 0xffff0000, v165
	v_pk_mul_f32 v[156:157], v[100:101], v[156:157]
	v_pk_mul_f32 v[158:159], v[102:103], v[158:159]
	v_lshlrev_b32_e32 v244, 16, v166
	v_and_b32_e32 v245, 0xffff0000, v166
	v_lshlrev_b32_e32 v246, 16, v167
	v_and_b32_e32 v247, 0xffff0000, v167
	v_pk_mul_f32 v[244:245], v[96:97], v[244:245]
	v_pk_mul_f32 v[246:247], v[98:99], v[246:247]
	v_lshlrev_b32_e32 v196, 16, v168
	v_and_b32_e32 v197, 0xffff0000, v168
	v_lshlrev_b32_e32 v198, 16, v169
	v_and_b32_e32 v199, 0xffff0000, v169
	v_pk_add_f32 v[156:157], v[156:157], v[196:197]
	v_pk_add_f32 v[158:159], v[158:159], v[198:199]
	v_lshlrev_b32_e32 v200, 16, v170
	v_and_b32_e32 v201, 0xffff0000, v170
	v_lshlrev_b32_e32 v204, 16, v171
	v_and_b32_e32 v205, 0xffff0000, v171
	v_pk_add_f32 v[244:245], v[244:245], v[200:201]
	v_pk_add_f32 v[246:247], v[246:247], v[204:205]
	v_cvt_pk_bf16_f32 v156, v156, v157
	v_cvt_pk_bf16_f32 v157, v158, v159
	v_cvt_pk_bf16_f32 v158, v244, v245
	v_cvt_pk_bf16_f32 v159, v246, v247
	v_add_u32_e32 v210, 0x30000, v163
	global_store_dwordx2 v210, v[156:157], s[6:7] offset:0
	global_store_dwordx2 v210, v[158:159], s[6:7] offset:32
	v_add_u32_e32 v146, 0x1c000, v160
	global_load_dwordx4 v[164:167], v146, s[0:1]
	v_add_u32_e32 v211, 0xa0000, v163
	global_load_dwordx2 v[168:169], v211, s[6:7] offset:256
	global_load_dwordx2 v[170:171], v211, s[6:7] offset:288
	s_waitcnt vmcnt(38)
	v_lshlrev_b32_e32 v156, 16, v172
	v_and_b32_e32 v157, 0xffff0000, v172
	v_lshlrev_b32_e32 v158, 16, v173
	v_and_b32_e32 v159, 0xffff0000, v173
	v_pk_mul_f32 v[156:157], v[92:93], v[156:157]
	v_pk_mul_f32 v[158:159], v[94:95], v[158:159]
	v_lshlrev_b32_e32 v244, 16, v174
	v_and_b32_e32 v245, 0xffff0000, v174
	v_lshlrev_b32_e32 v246, 16, v175
	v_and_b32_e32 v247, 0xffff0000, v175
	v_pk_mul_f32 v[244:245], v[88:89], v[244:245]
	v_pk_mul_f32 v[246:247], v[90:91], v[246:247]
	v_lshlrev_b32_e32 v196, 16, v176
	v_and_b32_e32 v197, 0xffff0000, v176
	v_lshlrev_b32_e32 v198, 16, v177
	v_and_b32_e32 v199, 0xffff0000, v177
	v_pk_add_f32 v[156:157], v[156:157], v[196:197]
	v_pk_add_f32 v[158:159], v[158:159], v[198:199]
	v_lshlrev_b32_e32 v200, 16, v178
	v_and_b32_e32 v201, 0xffff0000, v178
	v_lshlrev_b32_e32 v204, 16, v179
	v_and_b32_e32 v205, 0xffff0000, v179
	v_pk_add_f32 v[244:245], v[244:245], v[200:201]
	v_pk_add_f32 v[246:247], v[246:247], v[204:205]
	v_cvt_pk_bf16_f32 v156, v156, v157
	v_cvt_pk_bf16_f32 v157, v158, v159
	v_cvt_pk_bf16_f32 v158, v244, v245
	v_cvt_pk_bf16_f32 v159, v246, v247
	global_store_dwordx2 v163, v[156:157], s[6:7] offset:256
	global_store_dwordx2 v163, v[158:159], s[6:7] offset:288
	v_add_u32_e32 v147, 0x1e000, v160
	global_load_dwordx4 v[172:175], v147, s[0:1]
	v_add_u32_e32 v210, 0xb0000, v163
	global_load_dwordx2 v[176:177], v210, s[6:7] offset:256
	global_load_dwordx2 v[178:179], v210, s[6:7] offset:288
	s_waitcnt vmcnt(40)
	v_lshlrev_b32_e32 v156, 16, v180
	v_and_b32_e32 v157, 0xffff0000, v180
	v_lshlrev_b32_e32 v158, 16, v181
	v_and_b32_e32 v159, 0xffff0000, v181
	v_pk_mul_f32 v[156:157], v[84:85], v[156:157]
	v_pk_mul_f32 v[158:159], v[86:87], v[158:159]
	v_lshlrev_b32_e32 v244, 16, v182
	v_and_b32_e32 v245, 0xffff0000, v182
	v_lshlrev_b32_e32 v246, 16, v183
	v_and_b32_e32 v247, 0xffff0000, v183
	v_pk_mul_f32 v[244:245], v[80:81], v[244:245]
	v_pk_mul_f32 v[246:247], v[82:83], v[246:247]
	v_lshlrev_b32_e32 v196, 16, v184
	v_and_b32_e32 v197, 0xffff0000, v184
	v_lshlrev_b32_e32 v198, 16, v185
	v_and_b32_e32 v199, 0xffff0000, v185
	v_pk_add_f32 v[156:157], v[156:157], v[196:197]
	v_pk_add_f32 v[158:159], v[158:159], v[198:199]
	v_lshlrev_b32_e32 v200, 16, v186
	v_and_b32_e32 v201, 0xffff0000, v186
	v_lshlrev_b32_e32 v204, 16, v187
	v_and_b32_e32 v205, 0xffff0000, v187
	v_pk_add_f32 v[244:245], v[244:245], v[200:201]
	v_pk_add_f32 v[246:247], v[246:247], v[204:205]
	v_cvt_pk_bf16_f32 v156, v156, v157
	v_cvt_pk_bf16_f32 v157, v158, v159
	v_cvt_pk_bf16_f32 v158, v244, v245
	v_cvt_pk_bf16_f32 v159, v246, v247
	v_add_u32_e32 v211, 0x10000, v163
	global_store_dwordx2 v211, v[156:157], s[6:7] offset:256
	global_store_dwordx2 v211, v[158:159], s[6:7] offset:288
	s_waitcnt vmcnt(39)
; __device__ __forceinline__ float bflo(unsigned u) { return __uint_as_float(u << 16); }
; __device__ __forceinline__ float bfhi(unsigned u) { return __uint_as_float(u & 0xFFFF0000u); }
; __device__ __forceinline__ void phaseE(const Params& p, int layer) {
;     ...
;               uint4 g4[2]; uint2 old[2][2];
; #pragma unroll
;               for (int mm = 0; mm < 2; mm++) {
;                 const int m = mh * 2 + mm;
;                 g4[mm] = *(const uint4*)(gsb + ((ai * 2 + bj) * 4 + m) * 8192 + gs_lane);
;                 if (br) {
; #pragma unroll
;                   for (int n = 0; n < 2; n++)
;                     old[mm][n] = *(const uint2*)(mb + ((size_t)(ai * 128 + m * 16) * 2048 + bj * 128 + n * 16) * 2 + lane_m);
;                 }
;               }
; #pragma unroll
;               for (int mm = 0; mm < 2; mm++) {
;                 const int m = mh * 2 + mm;
;                 const unsigned gq[4] = {g4[mm].x, g4[mm].y, g4[mm].z, g4[mm].w};
; #pragma unroll
;                 for (int n = 0; n < 2; n++) {
;                   f32x4 v = acc[ai][bj][m][n];
;                   float o0 = bflo(gq[2 * n]) * v[0], o1 = bfhi(gq[2 * n]) * v[1], o2 = bflo(gq[2 * n + 1]) * v[2], o3 = bfhi(gq[2 * n + 1]) * v[3];
;                   char* mp = mb + ((size_t)(ai * 128 + m * 16) * 2048 + bj * 128 + n * 16) * 2 + lane_m;
;                   if (br) { o0 += bflo(old[mm][n].x); o1 += bfhi(old[mm][n].x); o2 += bflo(old[mm][n].y); o3 += bfhi(old[mm][n].y); }
;                   *(uint2*)mp = make_uint2(pk2(o0, o1), pk2(o2, o3));
;                 }
;               }
	v_lshlrev_b32_e32 v156, 16, v188
	v_and_b32_e32 v157, 0xffff0000, v188
	v_lshlrev_b32_e32 v158, 16, v189
	v_and_b32_e32 v159, 0xffff0000, v189
	v_pk_mul_f32 v[156:157], v[76:77], v[156:157]
	v_pk_mul_f32 v[158:159], v[78:79], v[158:159]
	v_lshlrev_b32_e32 v244, 16, v190
	v_and_b32_e32 v245, 0xffff0000, v190
	v_lshlrev_b32_e32 v246, 16, v191
	v_and_b32_e32 v247, 0xffff0000, v191
	v_pk_mul_f32 v[244:245], v[72:73], v[244:245]
	v_pk_mul_f32 v[246:247], v[74:75], v[246:247]
	v_lshlrev_b32_e32 v196, 16, v192
	v_and_b32_e32 v197, 0xffff0000, v192
	v_lshlrev_b32_e32 v198, 16, v193
	v_and_b32_e32 v199, 0xffff0000, v193
	v_pk_add_f32 v[156:157], v[156:157], v[196:197]
	v_pk_add_f32 v[158:159], v[158:159], v[198:199]
	v_lshlrev_b32_e32 v200, 16, v194
	v_and_b32_e32 v201, 0xffff0000, v194
	v_lshlrev_b32_e32 v204, 16, v195
	v_and_b32_e32 v205, 0xffff0000, v195
	v_pk_add_f32 v[244:245], v[244:245], v[200:201]
	v_pk_add_f32 v[246:247], v[246:247], v[204:205]
	v_cvt_pk_bf16_f32 v156, v156, v157
	v_cvt_pk_bf16_f32 v157, v158, v159
	v_cvt_pk_bf16_f32 v158, v244, v245
	v_cvt_pk_bf16_f32 v159, v246, v247
	v_add_u32_e32 v210, 0x20000, v163
	global_store_dwordx2 v210, v[156:157], s[6:7] offset:256
	global_store_dwordx2 v210, v[158:159], s[6:7] offset:288
	s_waitcnt vmcnt(38)
	v_lshlrev_b32_e32 v156, 16, v212
	v_and_b32_e32 v157, 0xffff0000, v212
	v_lshlrev_b32_e32 v158, 16, v213
	v_and_b32_e32 v159, 0xffff0000, v213
	v_pk_mul_f32 v[156:157], v[68:69], v[156:157]
	v_pk_mul_f32 v[158:159], v[70:71], v[158:159]
	v_lshlrev_b32_e32 v244, 16, v214
	v_and_b32_e32 v245, 0xffff0000, v214
	v_lshlrev_b32_e32 v246, 16, v215
	v_and_b32_e32 v247, 0xffff0000, v215
	v_pk_mul_f32 v[244:245], v[64:65], v[244:245]
	v_pk_mul_f32 v[246:247], v[66:67], v[246:247]
	v_lshlrev_b32_e32 v196, 16, v216
	v_and_b32_e32 v197, 0xffff0000, v216
	v_lshlrev_b32_e32 v198, 16, v217
	v_and_b32_e32 v199, 0xffff0000, v217
	v_pk_add_f32 v[156:157], v[156:157], v[196:197]
	v_pk_add_f32 v[158:159], v[158:159], v[198:199]
	v_lshlrev_b32_e32 v200, 16, v218
	v_and_b32_e32 v201, 0xffff0000, v218
	v_lshlrev_b32_e32 v204, 16, v219
	v_and_b32_e32 v205, 0xffff0000, v219
	v_pk_add_f32 v[244:245], v[244:245], v[200:201]
	v_pk_add_f32 v[246:247], v[246:247], v[204:205]
	v_cvt_pk_bf16_f32 v156, v156, v157
	v_cvt_pk_bf16_f32 v157, v158, v159
	v_cvt_pk_bf16_f32 v158, v244, v245
	v_cvt_pk_bf16_f32 v159, v246, v247
	v_add_u32_e32 v211, 0x30000, v163
	global_store_dwordx2 v211, v[156:157], s[6:7] offset:256
	global_store_dwordx2 v211, v[158:159], s[6:7] offset:288
	s_waitcnt vmcnt(37)
	v_lshlrev_b32_e32 v156, 16, v220
	v_and_b32_e32 v157, 0xffff0000, v220
	v_lshlrev_b32_e32 v158, 16, v221
	v_and_b32_e32 v159, 0xffff0000, v221
	v_pk_mul_f32 v[156:157], v[60:61], v[156:157]
	v_pk_mul_f32 v[158:159], v[62:63], v[158:159]
	v_lshlrev_b32_e32 v244, 16, v222
	v_and_b32_e32 v245, 0xffff0000, v222
	v_lshlrev_b32_e32 v246, 16, v223
	v_and_b32_e32 v247, 0xffff0000, v223
	v_pk_mul_f32 v[244:245], v[56:57], v[244:245]
	v_pk_mul_f32 v[246:247], v[58:59], v[246:247]
	v_lshlrev_b32_e32 v196, 16, v224
	v_and_b32_e32 v197, 0xffff0000, v224
	v_lshlrev_b32_e32 v198, 16, v225
	v_and_b32_e32 v199, 0xffff0000, v225
	v_pk_add_f32 v[156:157], v[156:157], v[196:197]
	v_pk_add_f32 v[158:159], v[158:159], v[198:199]
	v_lshlrev_b32_e32 v200, 16, v226
	v_and_b32_e32 v201, 0xffff0000, v226
	v_lshlrev_b32_e32 v204, 16, v227
	v_and_b32_e32 v205, 0xffff0000, v227
	v_pk_add_f32 v[244:245], v[244:245], v[200:201]
	v_pk_add_f32 v[246:247], v[246:247], v[204:205]
	v_cvt_pk_bf16_f32 v156, v156, v157
	v_cvt_pk_bf16_f32 v157, v158, v159
	v_cvt_pk_bf16_f32 v158, v244, v245
	v_cvt_pk_bf16_f32 v159, v246, v247
	v_add_u32_e32 v210, 0x80000, v163
	global_store_dwordx2 v210, v[156:157], s[6:7] offset:0
	global_store_dwordx2 v210, v[158:159], s[6:7] offset:32
	s_waitcnt vmcnt(36)
	v_lshlrev_b32_e32 v156, 16, v228
	v_and_b32_e32 v157, 0xffff0000, v228
	v_lshlrev_b32_e32 v158, 16, v229
	v_and_b32_e32 v159, 0xffff0000, v229
	v_pk_mul_f32 v[156:157], v[52:53], v[156:157]
	v_pk_mul_f32 v[158:159], v[54:55], v[158:159]
	v_lshlrev_b32_e32 v244, 16, v230
	v_and_b32_e32 v245, 0xffff0000, v230
	v_lshlrev_b32_e32 v246, 16, v231
	v_and_b32_e32 v247, 0xffff0000, v231
	v_pk_mul_f32 v[244:245], v[48:49], v[244:245]
	v_pk_mul_f32 v[246:247], v[50:51], v[246:247]
	v_lshlrev_b32_e32 v196, 16, v232
	v_and_b32_e32 v197, 0xffff0000, v232
	v_lshlrev_b32_e32 v198, 16, v233
	v_and_b32_e32 v199, 0xffff0000, v233
	v_pk_add_f32 v[156:157], v[156:157], v[196:197]
	v_pk_add_f32 v[158:159], v[158:159], v[198:199]
	v_lshlrev_b32_e32 v200, 16, v234
	v_and_b32_e32 v201, 0xffff0000, v234
	v_lshlrev_b32_e32 v204, 16, v235
	v_and_b32_e32 v205, 0xffff0000, v235
	v_pk_add_f32 v[244:245], v[244:245], v[200:201]
	v_pk_add_f32 v[246:247], v[246:247], v[204:205]
	v_cvt_pk_bf16_f32 v156, v156, v157
	v_cvt_pk_bf16_f32 v157, v158, v159
	v_cvt_pk_bf16_f32 v158, v244, v245
	v_cvt_pk_bf16_f32 v159, v246, v247
	v_add_u32_e32 v211, 0x90000, v163
	global_store_dwordx2 v211, v[156:157], s[6:7] offset:0
	global_store_dwordx2 v211, v[158:159], s[6:7] offset:32
	s_waitcnt vmcnt(35)
; __device__ __forceinline__ float bflo(unsigned u) { return __uint_as_float(u << 16); }
; __device__ __forceinline__ float bfhi(unsigned u) { return __uint_as_float(u & 0xFFFF0000u); }
; __device__ __forceinline__ void phaseE(const Params& p, int layer) {
;     ...
;               uint4 g4[2]; uint2 old[2][2];
; #pragma unroll
;               for (int mm = 0; mm < 2; mm++) {
;                 const int m = mh * 2 + mm;
;                 g4[mm] = *(const uint4*)(gsb + ((ai * 2 + bj) * 4 + m) * 8192 + gs_lane);
;                 if (br) {
; #pragma unroll
;                   for (int n = 0; n < 2; n++)
;                     old[mm][n] = *(const uint2*)(mb + ((size_t)(ai * 128 + m * 16) * 2048 + bj * 128 + n * 16) * 2 + lane_m);
;                 }
;               }
; #pragma unroll
;               for (int mm = 0; mm < 2; mm++) {
;                 const int m = mh * 2 + mm;
;                 const unsigned gq[4] = {g4[mm].x, g4[mm].y, g4[mm].z, g4[mm].w};
; #pragma unroll
;                 for (int n = 0; n < 2; n++) {
;                   f32x4 v = acc[ai][bj][m][n];
;                   float o0 = bflo(gq[2 * n]) * v[0], o1 = bfhi(gq[2 * n]) * v[1], o2 = bflo(gq[2 * n + 1]) * v[2], o3 = bfhi(gq[2 * n + 1]) * v[3];
;                   char* mp = mb + ((size_t)(ai * 128 + m * 16) * 2048 + bj * 128 + n * 16) * 2 + lane_m;
;                   if (br) { o0 += bflo(old[mm][n].x); o1 += bfhi(old[mm][n].x); o2 += bflo(old[mm][n].y); o3 += bfhi(old[mm][n].y); }
;                   *(uint2*)mp = make_uint2(pk2(o0, o1), pk2(o2, o3));
;                 }
;               }
	v_lshlrev_b32_e32 v156, 16, v236
	v_and_b32_e32 v157, 0xffff0000, v236
	v_lshlrev_b32_e32 v158, 16, v237
	v_and_b32_e32 v159, 0xffff0000, v237
	v_pk_mul_f32 v[156:157], v[44:45], v[156:157]
	v_pk_mul_f32 v[158:159], v[46:47], v[158:159]
	v_lshlrev_b32_e32 v244, 16, v238
	v_and_b32_e32 v245, 0xffff0000, v238
	v_lshlrev_b32_e32 v246, 16, v239
	v_and_b32_e32 v247, 0xffff0000, v239
	v_pk_mul_f32 v[244:245], v[40:41], v[244:245]
	v_pk_mul_f32 v[246:247], v[42:43], v[246:247]
	v_lshlrev_b32_e32 v196, 16, v240
	v_and_b32_e32 v197, 0xffff0000, v240
	v_lshlrev_b32_e32 v198, 16, v241
	v_and_b32_e32 v199, 0xffff0000, v241
	v_pk_add_f32 v[156:157], v[156:157], v[196:197]
	v_pk_add_f32 v[158:159], v[158:159], v[198:199]
	v_lshlrev_b32_e32 v200, 16, v242
	v_and_b32_e32 v201, 0xffff0000, v242
	v_lshlrev_b32_e32 v204, 16, v243
	v_and_b32_e32 v205, 0xffff0000, v243
	v_pk_add_f32 v[244:245], v[244:245], v[200:201]
	v_pk_add_f32 v[246:247], v[246:247], v[204:205]
	v_cvt_pk_bf16_f32 v156, v156, v157
	v_cvt_pk_bf16_f32 v157, v158, v159
	v_cvt_pk_bf16_f32 v158, v244, v245
	v_cvt_pk_bf16_f32 v159, v246, v247
	v_add_u32_e32 v210, 0xa0000, v163
	global_store_dwordx2 v210, v[156:157], s[6:7] offset:0
	global_store_dwordx2 v210, v[158:159], s[6:7] offset:32
	s_waitcnt vmcnt(32)
	v_lshlrev_b32_e32 v156, 16, v128
	v_and_b32_e32 v157, 0xffff0000, v128
	v_lshlrev_b32_e32 v158, 16, v129
	v_and_b32_e32 v159, 0xffff0000, v129
	v_pk_mul_f32 v[156:157], v[36:37], v[156:157]
	v_pk_mul_f32 v[158:159], v[38:39], v[158:159]
	v_lshlrev_b32_e32 v244, 16, v130
	v_and_b32_e32 v245, 0xffff0000, v130
	v_lshlrev_b32_e32 v246, 16, v131
	v_and_b32_e32 v247, 0xffff0000, v131
	v_pk_mul_f32 v[244:245], v[32:33], v[244:245]
	v_pk_mul_f32 v[246:247], v[34:35], v[246:247]
	v_lshlrev_b32_e32 v196, 16, v132
	v_and_b32_e32 v197, 0xffff0000, v132
	v_lshlrev_b32_e32 v198, 16, v133
	v_and_b32_e32 v199, 0xffff0000, v133
	v_pk_add_f32 v[156:157], v[156:157], v[196:197]
	v_pk_add_f32 v[158:159], v[158:159], v[198:199]
	v_lshlrev_b32_e32 v200, 16, v134
	v_and_b32_e32 v201, 0xffff0000, v134
	v_lshlrev_b32_e32 v204, 16, v135
	v_and_b32_e32 v205, 0xffff0000, v135
	v_pk_add_f32 v[244:245], v[244:245], v[200:201]
	v_pk_add_f32 v[246:247], v[246:247], v[204:205]
	v_cvt_pk_bf16_f32 v156, v156, v157
	v_cvt_pk_bf16_f32 v157, v158, v159
	v_cvt_pk_bf16_f32 v158, v244, v245
	v_cvt_pk_bf16_f32 v159, v246, v247
	v_add_u32_e32 v211, 0xb0000, v163
	global_store_dwordx2 v211, v[156:157], s[6:7] offset:0
	global_store_dwordx2 v211, v[158:159], s[6:7] offset:32
	s_waitcnt vmcnt(29)
	v_lshlrev_b32_e32 v156, 16, v136
	v_and_b32_e32 v157, 0xffff0000, v136
	v_lshlrev_b32_e32 v158, 16, v137
	v_and_b32_e32 v159, 0xffff0000, v137
	v_pk_mul_f32 v[156:157], v[28:29], v[156:157]
	v_pk_mul_f32 v[158:159], v[30:31], v[158:159]
	v_lshlrev_b32_e32 v244, 16, v138
	v_and_b32_e32 v245, 0xffff0000, v138
	v_lshlrev_b32_e32 v246, 16, v139
	v_and_b32_e32 v247, 0xffff0000, v139
	v_pk_mul_f32 v[244:245], v[24:25], v[244:245]
	v_pk_mul_f32 v[246:247], v[26:27], v[246:247]
	v_lshlrev_b32_e32 v196, 16, v140
	v_and_b32_e32 v197, 0xffff0000, v140
	v_lshlrev_b32_e32 v198, 16, v141
	v_and_b32_e32 v199, 0xffff0000, v141
	v_pk_add_f32 v[156:157], v[156:157], v[196:197]
	v_pk_add_f32 v[158:159], v[158:159], v[198:199]
	v_lshlrev_b32_e32 v200, 16, v142
	v_and_b32_e32 v201, 0xffff0000, v142
	v_lshlrev_b32_e32 v204, 16, v143
	v_and_b32_e32 v205, 0xffff0000, v143
	v_pk_add_f32 v[244:245], v[244:245], v[200:201]
	v_pk_add_f32 v[246:247], v[246:247], v[204:205]
	v_cvt_pk_bf16_f32 v156, v156, v157
	v_cvt_pk_bf16_f32 v157, v158, v159
	v_cvt_pk_bf16_f32 v158, v244, v245
	v_cvt_pk_bf16_f32 v159, v246, v247
	v_add_u32_e32 v210, 0x80000, v163
	global_store_dwordx2 v210, v[156:157], s[6:7] offset:256
	global_store_dwordx2 v210, v[158:159], s[6:7] offset:288
	s_waitcnt vmcnt(26)
	v_lshlrev_b32_e32 v156, 16, v148
	v_and_b32_e32 v157, 0xffff0000, v148
	v_lshlrev_b32_e32 v158, 16, v149
	v_and_b32_e32 v159, 0xffff0000, v149
	v_pk_mul_f32 v[156:157], v[20:21], v[156:157]
	v_pk_mul_f32 v[158:159], v[22:23], v[158:159]
	v_lshlrev_b32_e32 v244, 16, v150
	v_and_b32_e32 v245, 0xffff0000, v150
	v_lshlrev_b32_e32 v246, 16, v151
	v_and_b32_e32 v247, 0xffff0000, v151
	v_pk_mul_f32 v[244:245], v[16:17], v[244:245]
	v_pk_mul_f32 v[246:247], v[18:19], v[246:247]
	v_lshlrev_b32_e32 v196, 16, v152
	v_and_b32_e32 v197, 0xffff0000, v152
	v_lshlrev_b32_e32 v198, 16, v153
	v_and_b32_e32 v199, 0xffff0000, v153
	v_pk_add_f32 v[156:157], v[156:157], v[196:197]
	v_pk_add_f32 v[158:159], v[158:159], v[198:199]
	v_lshlrev_b32_e32 v200, 16, v154
	v_and_b32_e32 v201, 0xffff0000, v154
	v_lshlrev_b32_e32 v204, 16, v155
	v_and_b32_e32 v205, 0xffff0000, v155
	v_pk_add_f32 v[244:245], v[244:245], v[200:201]
	v_pk_add_f32 v[246:247], v[246:247], v[204:205]
	v_cvt_pk_bf16_f32 v156, v156, v157
	v_cvt_pk_bf16_f32 v157, v158, v159
	v_cvt_pk_bf16_f32 v158, v244, v245
	v_cvt_pk_bf16_f32 v159, v246, v247
	v_add_u32_e32 v211, 0x90000, v163
	global_store_dwordx2 v211, v[156:157], s[6:7] offset:256
	global_store_dwordx2 v211, v[158:159], s[6:7] offset:288
	s_waitcnt vmcnt(23)
; __device__ __forceinline__ float bflo(unsigned u) { return __uint_as_float(u << 16); }
; __device__ __forceinline__ float bfhi(unsigned u) { return __uint_as_float(u & 0xFFFF0000u); }
; __device__ __forceinline__ void phaseE(const Params& p, int layer) {
;     ...
;               uint4 g4[2]; uint2 old[2][2];
; #pragma unroll
;               for (int mm = 0; mm < 2; mm++) {
;                 const int m = mh * 2 + mm;
;                 g4[mm] = *(const uint4*)(gsb + ((ai * 2 + bj) * 4 + m) * 8192 + gs_lane);
;                 if (br) {
; #pragma unroll
;                   for (int n = 0; n < 2; n++)
;                     old[mm][n] = *(const uint2*)(mb + ((size_t)(ai * 128 + m * 16) * 2048 + bj * 128 + n * 16) * 2 + lane_m);
;                 }
;               }
; #pragma unroll
;               for (int mm = 0; mm < 2; mm++) {
;                 const int m = mh * 2 + mm;
;                 const unsigned gq[4] = {g4[mm].x, g4[mm].y, g4[mm].z, g4[mm].w};
; #pragma unroll
;                 for (int n = 0; n < 2; n++) {
;                   f32x4 v = acc[ai][bj][m][n];
;                   float o0 = bflo(gq[2 * n]) * v[0], o1 = bfhi(gq[2 * n]) * v[1], o2 = bflo(gq[2 * n + 1]) * v[2], o3 = bfhi(gq[2 * n + 1]) * v[3];
;                   char* mp = mb + ((size_t)(ai * 128 + m * 16) * 2048 + bj * 128 + n * 16) * 2 + lane_m;
;                   if (br) { o0 += bflo(old[mm][n].x); o1 += bfhi(old[mm][n].x); o2 += bflo(old[mm][n].y); o3 += bfhi(old[mm][n].y); }
;                   *(uint2*)mp = make_uint2(pk2(o0, o1), pk2(o2, o3));
;                 }
;               }
	v_lshlrev_b32_e32 v156, 16, v164
	v_and_b32_e32 v157, 0xffff0000, v164
	v_lshlrev_b32_e32 v158, 16, v165
	v_and_b32_e32 v159, 0xffff0000, v165
	v_pk_mul_f32 v[156:157], v[12:13], v[156:157]
	v_pk_mul_f32 v[158:159], v[14:15], v[158:159]
	v_lshlrev_b32_e32 v244, 16, v166
	v_and_b32_e32 v245, 0xffff0000, v166
	v_lshlrev_b32_e32 v246, 16, v167
	v_and_b32_e32 v247, 0xffff0000, v167
	v_pk_mul_f32 v[244:245], v[8:9], v[244:245]
	v_pk_mul_f32 v[246:247], v[10:11], v[246:247]
	v_lshlrev_b32_e32 v196, 16, v168
	v_and_b32_e32 v197, 0xffff0000, v168
	v_lshlrev_b32_e32 v198, 16, v169
	v_and_b32_e32 v199, 0xffff0000, v169
	v_pk_add_f32 v[156:157], v[156:157], v[196:197]
	v_pk_add_f32 v[158:159], v[158:159], v[198:199]
	v_lshlrev_b32_e32 v200, 16, v170
	v_and_b32_e32 v201, 0xffff0000, v170
	v_lshlrev_b32_e32 v204, 16, v171
	v_and_b32_e32 v205, 0xffff0000, v171
	v_pk_add_f32 v[244:245], v[244:245], v[200:201]
	v_pk_add_f32 v[246:247], v[246:247], v[204:205]
	v_cvt_pk_bf16_f32 v156, v156, v157
	v_cvt_pk_bf16_f32 v157, v158, v159
	v_cvt_pk_bf16_f32 v158, v244, v245
	v_cvt_pk_bf16_f32 v159, v246, v247
	v_add_u32_e32 v210, 0xa0000, v163
	global_store_dwordx2 v210, v[156:157], s[6:7] offset:256
	global_store_dwordx2 v210, v[158:159], s[6:7] offset:288
	s_waitcnt vmcnt(20)
	v_lshlrev_b32_e32 v156, 16, v172
	v_and_b32_e32 v157, 0xffff0000, v172
	v_lshlrev_b32_e32 v158, 16, v173
	v_and_b32_e32 v159, 0xffff0000, v173
	v_pk_mul_f32 v[156:157], v[4:5], v[156:157]
	v_pk_mul_f32 v[158:159], v[6:7], v[158:159]
	v_lshlrev_b32_e32 v244, 16, v174
	v_and_b32_e32 v245, 0xffff0000, v174
	v_lshlrev_b32_e32 v246, 16, v175
	v_and_b32_e32 v247, 0xffff0000, v175
	v_pk_mul_f32 v[244:245], v[0:1], v[244:245]
	v_pk_mul_f32 v[246:247], v[2:3], v[246:247]
	v_lshlrev_b32_e32 v196, 16, v176
	v_and_b32_e32 v197, 0xffff0000, v176
	v_lshlrev_b32_e32 v198, 16, v177
	v_and_b32_e32 v199, 0xffff0000, v177
	v_pk_add_f32 v[156:157], v[156:157], v[196:197]
	v_pk_add_f32 v[158:159], v[158:159], v[198:199]
	v_lshlrev_b32_e32 v200, 16, v178
	v_and_b32_e32 v201, 0xffff0000, v178
	v_lshlrev_b32_e32 v204, 16, v179
	v_and_b32_e32 v205, 0xffff0000, v179
	v_pk_add_f32 v[244:245], v[244:245], v[200:201]
	v_pk_add_f32 v[246:247], v[246:247], v[204:205]
	v_cvt_pk_bf16_f32 v156, v156, v157
	v_cvt_pk_bf16_f32 v157, v158, v159
	v_cvt_pk_bf16_f32 v158, v244, v245
	v_cvt_pk_bf16_f32 v159, v246, v247
	v_add_u32_e32 v211, 0xb0000, v163
	global_store_dwordx2 v211, v[156:157], s[6:7] offset:256
	global_store_dwordx2 v211, v[158:159], s[6:7] offset:288
	s_branch .LBB0_2313
.Lbrepi_first:
	ds_read_b128 v[128:131], v165
	ds_read_b128 v[136:139], v165 offset:8192
	ds_read_b128 v[148:151], v165 offset:16384
	ds_read_b128 v[164:167], v165 offset:24576
	v_add_u32_e32 v146, 0x8000, v160
	global_load_dwordx4 v[172:175], v146, s[0:1]
	v_add_u32_e32 v147, 0xa000, v160
	global_load_dwordx4 v[180:183], v147, s[0:1]
	v_add_u32_e32 v146, 0xc000, v160
	global_load_dwordx4 v[188:191], v146, s[0:1]
	v_add_u32_e32 v147, 0xe000, v160
	global_load_dwordx4 v[212:215], v147, s[0:1]
	v_add_u32_e32 v146, 0x10000, v160
	global_load_dwordx4 v[220:223], v146, s[0:1]
	v_add_u32_e32 v147, 0x12000, v160
	global_load_dwordx4 v[228:231], v147, s[0:1]
	v_add_u32_e32 v146, 0x14000, v160
	global_load_dwordx4 v[236:239], v146, s[0:1]
	s_waitcnt lgkmcnt(0)
	v_lshlrev_b32_e32 v156, 16, v128
	v_and_b32_e32 v157, 0xffff0000, v128
	v_lshlrev_b32_e32 v158, 16, v129
	v_and_b32_e32 v159, 0xffff0000, v129
	v_pk_mul_f32 v[156:157], v[124:125], v[156:157]
	v_pk_mul_f32 v[158:159], v[126:127], v[158:159]
	v_lshlrev_b32_e32 v244, 16, v130
	v_and_b32_e32 v245, 0xffff0000, v130
	v_lshlrev_b32_e32 v246, 16, v131
	v_and_b32_e32 v247, 0xffff0000, v131
	v_pk_mul_f32 v[244:245], v[120:121], v[244:245]
	v_pk_mul_f32 v[246:247], v[122:123], v[246:247]
	v_cvt_pk_bf16_f32 v156, v156, v157
	v_cvt_pk_bf16_f32 v157, v158, v159
	v_cvt_pk_bf16_f32 v158, v244, v245
	v_cvt_pk_bf16_f32 v159, v246, v247
	global_store_dwordx2 v163, v[156:157], s[6:7] offset:0
	global_store_dwordx2 v163, v[158:159], s[6:7] offset:32
	v_add_u32_e32 v147, 0x16000, v160
	global_load_dwordx4 v[128:131], v147, s[0:1]
	s_waitcnt lgkmcnt(0)
	v_lshlrev_b32_e32 v156, 16, v136
	v_and_b32_e32 v157, 0xffff0000, v136
	v_lshlrev_b32_e32 v158, 16, v137
	v_and_b32_e32 v159, 0xffff0000, v137
	v_pk_mul_f32 v[156:157], v[116:117], v[156:157]
	v_pk_mul_f32 v[158:159], v[118:119], v[158:159]
	v_lshlrev_b32_e32 v244, 16, v138
	v_and_b32_e32 v245, 0xffff0000, v138
	v_lshlrev_b32_e32 v246, 16, v139
	v_and_b32_e32 v247, 0xffff0000, v139
	v_pk_mul_f32 v[244:245], v[112:113], v[244:245]
	v_pk_mul_f32 v[246:247], v[114:115], v[246:247]
	v_cvt_pk_bf16_f32 v156, v156, v157
	v_cvt_pk_bf16_f32 v157, v158, v159
	v_cvt_pk_bf16_f32 v158, v244, v245
	v_cvt_pk_bf16_f32 v159, v246, v247
	v_add_u32_e32 v210, 0x10000, v163
	global_store_dwordx2 v210, v[156:157], s[6:7] offset:0
	global_store_dwordx2 v210, v[158:159], s[6:7] offset:32
	v_add_u32_e32 v146, 0x18000, v160
	global_load_dwordx4 v[136:139], v146, s[0:1]
	s_waitcnt lgkmcnt(0)
	v_lshlrev_b32_e32 v156, 16, v148
	v_and_b32_e32 v157, 0xffff0000, v148
	v_lshlrev_b32_e32 v158, 16, v149
	v_and_b32_e32 v159, 0xffff0000, v149
	v_pk_mul_f32 v[156:157], v[108:109], v[156:157]
	v_pk_mul_f32 v[158:159], v[110:111], v[158:159]
	v_lshlrev_b32_e32 v244, 16, v150
	v_and_b32_e32 v245, 0xffff0000, v150
	v_lshlrev_b32_e32 v246, 16, v151
	v_and_b32_e32 v247, 0xffff0000, v151
	v_pk_mul_f32 v[244:245], v[104:105], v[244:245]
	v_pk_mul_f32 v[246:247], v[106:107], v[246:247]
	v_cvt_pk_bf16_f32 v156, v156, v157
	v_cvt_pk_bf16_f32 v157, v158, v159
	v_cvt_pk_bf16_f32 v158, v244, v245
	v_cvt_pk_bf16_f32 v159, v246, v247
	v_add_u32_e32 v211, 0x20000, v163
	global_store_dwordx2 v211, v[156:157], s[6:7] offset:0
	global_store_dwordx2 v211, v[158:159], s[6:7] offset:32
	v_add_u32_e32 v147, 0x1a000, v160
	global_load_dwordx4 v[148:151], v147, s[0:1]
	s_waitcnt lgkmcnt(0)
; __device__ __forceinline__ float bflo(unsigned u) { return __uint_as_float(u << 16); }
; __device__ __forceinline__ float bfhi(unsigned u) { return __uint_as_float(u & 0xFFFF0000u); }
; __device__ __forceinline__ void phaseE(const Params& p, int layer) {
;     ...
;               uint4 g4[2]; uint2 old[2][2];
; #pragma unroll
;               for (int mm = 0; mm < 2; mm++) {
;                 const int m = mh * 2 + mm;
;                 g4[mm] = *(const uint4*)(gsb + ((ai * 2 + bj) * 4 + m) * 8192 + gs_lane);
;                 if (br) {
; #pragma unroll
;                   for (int n = 0; n < 2; n++)
;                     old[mm][n] = *(const uint2*)(mb + ((size_t)(ai * 128 + m * 16) * 2048 + bj * 128 + n * 16) * 2 + lane_m);
;                 }
;               }
; #pragma unroll
;               for (int mm = 0; mm < 2; mm++) {
;                 const int m = mh * 2 + mm;
;                 const unsigned gq[4] = {g4[mm].x, g4[mm].y, g4[mm].z, g4[mm].w};
; #pragma unroll
;                 for (int n = 0; n < 2; n++) {
;                   f32x4 v = acc[ai][bj][m][n];
;                   float o0 = bflo(gq[2 * n]) * v[0], o1 = bfhi(gq[2 * n]) * v[1], o2 = bflo(gq[2 * n + 1]) * v[2], o3 = bfhi(gq[2 * n + 1]) * v[3];
;                   char* mp = mb + ((size_t)(ai * 128 + m * 16) * 2048 + bj * 128 + n * 16) * 2 + lane_m;
;                   if (br) { o0 += bflo(old[mm][n].x); o1 += bfhi(old[mm][n].x); o2 += bflo(old[mm][n].y); o3 += bfhi(old[mm][n].y); }
;                   *(uint2*)mp = make_uint2(pk2(o0, o1), pk2(o2, o3));
;                 }
;               }
	v_lshlrev_b32_e32 v156, 16, v164
	v_and_b32_e32 v157, 0xffff0000, v164
	v_lshlrev_b32_e32 v158, 16, v165
	v_and_b32_e32 v159, 0xffff0000, v165
	v_pk_mul_f32 v[156:157], v[100:101], v[156:157]
	v_pk_mul_f32 v[158:159], v[102:103], v[158:159]
	v_lshlrev_b32_e32 v244, 16, v166
	v_and_b32_e32 v245, 0xffff0000, v166
	v_lshlrev_b32_e32 v246, 16, v167
	v_and_b32_e32 v247, 0xffff0000, v167
	v_pk_mul_f32 v[244:245], v[96:97], v[244:245]
	v_pk_mul_f32 v[246:247], v[98:99], v[246:247]
	v_cvt_pk_bf16_f32 v156, v156, v157
	v_cvt_pk_bf16_f32 v157, v158, v159
	v_cvt_pk_bf16_f32 v158, v244, v245
	v_cvt_pk_bf16_f32 v159, v246, v247
	v_add_u32_e32 v210, 0x30000, v163
	global_store_dwordx2 v210, v[156:157], s[6:7] offset:0
	global_store_dwordx2 v210, v[158:159], s[6:7] offset:32
	v_add_u32_e32 v146, 0x1c000, v160
	global_load_dwordx4 v[164:167], v146, s[0:1]
	s_waitcnt vmcnt(18)
	v_lshlrev_b32_e32 v156, 16, v172
	v_and_b32_e32 v157, 0xffff0000, v172
	v_lshlrev_b32_e32 v158, 16, v173
	v_and_b32_e32 v159, 0xffff0000, v173
	v_pk_mul_f32 v[156:157], v[92:93], v[156:157]
	v_pk_mul_f32 v[158:159], v[94:95], v[158:159]
	v_lshlrev_b32_e32 v244, 16, v174
	v_and_b32_e32 v245, 0xffff0000, v174
	v_lshlrev_b32_e32 v246, 16, v175
	v_and_b32_e32 v247, 0xffff0000, v175
	v_pk_mul_f32 v[244:245], v[88:89], v[244:245]
	v_pk_mul_f32 v[246:247], v[90:91], v[246:247]
	v_cvt_pk_bf16_f32 v156, v156, v157
	v_cvt_pk_bf16_f32 v157, v158, v159
	v_cvt_pk_bf16_f32 v158, v244, v245
	v_cvt_pk_bf16_f32 v159, v246, v247
	global_store_dwordx2 v163, v[156:157], s[6:7] offset:256
	global_store_dwordx2 v163, v[158:159], s[6:7] offset:288
	v_add_u32_e32 v147, 0x1e000, v160
	global_load_dwordx4 v[172:175], v147, s[0:1]
	s_waitcnt vmcnt(20)
	v_lshlrev_b32_e32 v156, 16, v180
	v_and_b32_e32 v157, 0xffff0000, v180
	v_lshlrev_b32_e32 v158, 16, v181
	v_and_b32_e32 v159, 0xffff0000, v181
	v_pk_mul_f32 v[156:157], v[84:85], v[156:157]
	v_pk_mul_f32 v[158:159], v[86:87], v[158:159]
	v_lshlrev_b32_e32 v244, 16, v182
	v_and_b32_e32 v245, 0xffff0000, v182
	v_lshlrev_b32_e32 v246, 16, v183
	v_and_b32_e32 v247, 0xffff0000, v183
	v_pk_mul_f32 v[244:245], v[80:81], v[244:245]
	v_pk_mul_f32 v[246:247], v[82:83], v[246:247]
	v_cvt_pk_bf16_f32 v156, v156, v157
	v_cvt_pk_bf16_f32 v157, v158, v159
	v_cvt_pk_bf16_f32 v158, v244, v245
	v_cvt_pk_bf16_f32 v159, v246, v247
	v_add_u32_e32 v211, 0x10000, v163
	global_store_dwordx2 v211, v[156:157], s[6:7] offset:256
	global_store_dwordx2 v211, v[158:159], s[6:7] offset:288
	s_waitcnt vmcnt(21)
	v_lshlrev_b32_e32 v156, 16, v188
	v_and_b32_e32 v157, 0xffff0000, v188
	v_lshlrev_b32_e32 v158, 16, v189
	v_and_b32_e32 v159, 0xffff0000, v189
	v_pk_mul_f32 v[156:157], v[76:77], v[156:157]
	v_pk_mul_f32 v[158:159], v[78:79], v[158:159]
	v_lshlrev_b32_e32 v244, 16, v190
	v_and_b32_e32 v245, 0xffff0000, v190
	v_lshlrev_b32_e32 v246, 16, v191
	v_and_b32_e32 v247, 0xffff0000, v191
	v_pk_mul_f32 v[244:245], v[72:73], v[244:245]
	v_pk_mul_f32 v[246:247], v[74:75], v[246:247]
	v_cvt_pk_bf16_f32 v156, v156, v157
	v_cvt_pk_bf16_f32 v157, v158, v159
	v_cvt_pk_bf16_f32 v158, v244, v245
	v_cvt_pk_bf16_f32 v159, v246, v247
	v_add_u32_e32 v210, 0x20000, v163
	global_store_dwordx2 v210, v[156:157], s[6:7] offset:256
	global_store_dwordx2 v210, v[158:159], s[6:7] offset:288
	s_waitcnt vmcnt(22)
	v_lshlrev_b32_e32 v156, 16, v212
	v_and_b32_e32 v157, 0xffff0000, v212
	v_lshlrev_b32_e32 v158, 16, v213
	v_and_b32_e32 v159, 0xffff0000, v213
	v_pk_mul_f32 v[156:157], v[68:69], v[156:157]
	v_pk_mul_f32 v[158:159], v[70:71], v[158:159]
	v_lshlrev_b32_e32 v244, 16, v214
	v_and_b32_e32 v245, 0xffff0000, v214
	v_lshlrev_b32_e32 v246, 16, v215
	v_and_b32_e32 v247, 0xffff0000, v215
	v_pk_mul_f32 v[244:245], v[64:65], v[244:245]
	v_pk_mul_f32 v[246:247], v[66:67], v[246:247]
	v_cvt_pk_bf16_f32 v156, v156, v157
	v_cvt_pk_bf16_f32 v157, v158, v159
	v_cvt_pk_bf16_f32 v158, v244, v245
	v_cvt_pk_bf16_f32 v159, v246, v247
	v_add_u32_e32 v211, 0x30000, v163
	global_store_dwordx2 v211, v[156:157], s[6:7] offset:256
	global_store_dwordx2 v211, v[158:159], s[6:7] offset:288
	s_waitcnt vmcnt(23)
	v_lshlrev_b32_e32 v156, 16, v220
	v_and_b32_e32 v157, 0xffff0000, v220
	v_lshlrev_b32_e32 v158, 16, v221
	v_and_b32_e32 v159, 0xffff0000, v221
	v_pk_mul_f32 v[156:157], v[60:61], v[156:157]
	v_pk_mul_f32 v[158:159], v[62:63], v[158:159]
	v_lshlrev_b32_e32 v244, 16, v222
	v_and_b32_e32 v245, 0xffff0000, v222
	v_lshlrev_b32_e32 v246, 16, v223
	v_and_b32_e32 v247, 0xffff0000, v223
	v_pk_mul_f32 v[244:245], v[56:57], v[244:245]
	v_pk_mul_f32 v[246:247], v[58:59], v[246:247]
	v_cvt_pk_bf16_f32 v156, v156, v157
	v_cvt_pk_bf16_f32 v157, v158, v159
	v_cvt_pk_bf16_f32 v158, v244, v245
	v_cvt_pk_bf16_f32 v159, v246, v247
	v_add_u32_e32 v210, 0x80000, v163
	global_store_dwordx2 v210, v[156:157], s[6:7] offset:0
	global_store_dwordx2 v210, v[158:159], s[6:7] offset:32
	s_waitcnt vmcnt(24)
; __device__ __forceinline__ float bflo(unsigned u) { return __uint_as_float(u << 16); }
; __device__ __forceinline__ float bfhi(unsigned u) { return __uint_as_float(u & 0xFFFF0000u); }
; __device__ __forceinline__ void phaseE(const Params& p, int layer) {
;     ...
;               uint4 g4[2]; uint2 old[2][2];
; #pragma unroll
;               for (int mm = 0; mm < 2; mm++) {
;                 const int m = mh * 2 + mm;
;                 g4[mm] = *(const uint4*)(gsb + ((ai * 2 + bj) * 4 + m) * 8192 + gs_lane);
;                 if (br) {
; #pragma unroll
;                   for (int n = 0; n < 2; n++)
;                     old[mm][n] = *(const uint2*)(mb + ((size_t)(ai * 128 + m * 16) * 2048 + bj * 128 + n * 16) * 2 + lane_m);
;                 }
;               }
; #pragma unroll
;               for (int mm = 0; mm < 2; mm++) {
;                 const int m = mh * 2 + mm;
;                 const unsigned gq[4] = {g4[mm].x, g4[mm].y, g4[mm].z, g4[mm].w};
; #pragma unroll
;                 for (int n = 0; n < 2; n++) {
;                   f32x4 v = acc[ai][bj][m][n];
;                   float o0 = bflo(gq[2 * n]) * v[0], o1 = bfhi(gq[2 * n]) * v[1], o2 = bflo(gq[2 * n + 1]) * v[2], o3 = bfhi(gq[2 * n + 1]) * v[3];
;                   char* mp = mb + ((size_t)(ai * 128 + m * 16) * 2048 + bj * 128 + n * 16) * 2 + lane_m;
;                   if (br) { o0 += bflo(old[mm][n].x); o1 += bfhi(old[mm][n].x); o2 += bflo(old[mm][n].y); o3 += bfhi(old[mm][n].y); }
;                   *(uint2*)mp = make_uint2(pk2(o0, o1), pk2(o2, o3));
;                 }
;               }
	v_lshlrev_b32_e32 v156, 16, v228
	v_and_b32_e32 v157, 0xffff0000, v228
	v_lshlrev_b32_e32 v158, 16, v229
	v_and_b32_e32 v159, 0xffff0000, v229
	v_pk_mul_f32 v[156:157], v[52:53], v[156:157]
	v_pk_mul_f32 v[158:159], v[54:55], v[158:159]
	v_lshlrev_b32_e32 v244, 16, v230
	v_and_b32_e32 v245, 0xffff0000, v230
	v_lshlrev_b32_e32 v246, 16, v231
	v_and_b32_e32 v247, 0xffff0000, v231
	v_pk_mul_f32 v[244:245], v[48:49], v[244:245]
	v_pk_mul_f32 v[246:247], v[50:51], v[246:247]
	v_cvt_pk_bf16_f32 v156, v156, v157
	v_cvt_pk_bf16_f32 v157, v158, v159
	v_cvt_pk_bf16_f32 v158, v244, v245
	v_cvt_pk_bf16_f32 v159, v246, v247
	v_add_u32_e32 v211, 0x90000, v163
	global_store_dwordx2 v211, v[156:157], s[6:7] offset:0
	global_store_dwordx2 v211, v[158:159], s[6:7] offset:32
	s_waitcnt vmcnt(25)
	v_lshlrev_b32_e32 v156, 16, v236
	v_and_b32_e32 v157, 0xffff0000, v236
	v_lshlrev_b32_e32 v158, 16, v237
	v_and_b32_e32 v159, 0xffff0000, v237
	v_pk_mul_f32 v[156:157], v[44:45], v[156:157]
	v_pk_mul_f32 v[158:159], v[46:47], v[158:159]
	v_lshlrev_b32_e32 v244, 16, v238
	v_and_b32_e32 v245, 0xffff0000, v238
	v_lshlrev_b32_e32 v246, 16, v239
	v_and_b32_e32 v247, 0xffff0000, v239
	v_pk_mul_f32 v[244:245], v[40:41], v[244:245]
	v_pk_mul_f32 v[246:247], v[42:43], v[246:247]
	v_cvt_pk_bf16_f32 v156, v156, v157
	v_cvt_pk_bf16_f32 v157, v158, v159
	v_cvt_pk_bf16_f32 v158, v244, v245
	v_cvt_pk_bf16_f32 v159, v246, v247
	v_add_u32_e32 v210, 0xa0000, v163
	global_store_dwordx2 v210, v[156:157], s[6:7] offset:0
	global_store_dwordx2 v210, v[158:159], s[6:7] offset:32
	s_waitcnt vmcnt(24)
	v_lshlrev_b32_e32 v156, 16, v128
	v_and_b32_e32 v157, 0xffff0000, v128
	v_lshlrev_b32_e32 v158, 16, v129
	v_and_b32_e32 v159, 0xffff0000, v129
	v_pk_mul_f32 v[156:157], v[36:37], v[156:157]
	v_pk_mul_f32 v[158:159], v[38:39], v[158:159]
	v_lshlrev_b32_e32 v244, 16, v130
	v_and_b32_e32 v245, 0xffff0000, v130
	v_lshlrev_b32_e32 v246, 16, v131
	v_and_b32_e32 v247, 0xffff0000, v131
	v_pk_mul_f32 v[244:245], v[32:33], v[244:245]
	v_pk_mul_f32 v[246:247], v[34:35], v[246:247]
	v_cvt_pk_bf16_f32 v156, v156, v157
	v_cvt_pk_bf16_f32 v157, v158, v159
	v_cvt_pk_bf16_f32 v158, v244, v245
	v_cvt_pk_bf16_f32 v159, v246, v247
	v_add_u32_e32 v211, 0xb0000, v163
	global_store_dwordx2 v211, v[156:157], s[6:7] offset:0
	global_store_dwordx2 v211, v[158:159], s[6:7] offset:32
	s_waitcnt vmcnt(23)
	v_lshlrev_b32_e32 v156, 16, v136
	v_and_b32_e32 v157, 0xffff0000, v136
	v_lshlrev_b32_e32 v158, 16, v137
	v_and_b32_e32 v159, 0xffff0000, v137
	v_pk_mul_f32 v[156:157], v[28:29], v[156:157]
	v_pk_mul_f32 v[158:159], v[30:31], v[158:159]
	v_lshlrev_b32_e32 v244, 16, v138
	v_and_b32_e32 v245, 0xffff0000, v138
	v_lshlrev_b32_e32 v246, 16, v139
	v_and_b32_e32 v247, 0xffff0000, v139
	v_pk_mul_f32 v[244:245], v[24:25], v[244:245]
	v_pk_mul_f32 v[246:247], v[26:27], v[246:247]
	v_cvt_pk_bf16_f32 v156, v156, v157
	v_cvt_pk_bf16_f32 v157, v158, v159
	v_cvt_pk_bf16_f32 v158, v244, v245
	v_cvt_pk_bf16_f32 v159, v246, v247
	v_add_u32_e32 v210, 0x80000, v163
	global_store_dwordx2 v210, v[156:157], s[6:7] offset:256
	global_store_dwordx2 v210, v[158:159], s[6:7] offset:288
	s_waitcnt vmcnt(22)
	v_lshlrev_b32_e32 v156, 16, v148
	v_and_b32_e32 v157, 0xffff0000, v148
	v_lshlrev_b32_e32 v158, 16, v149
	v_and_b32_e32 v159, 0xffff0000, v149
	v_pk_mul_f32 v[156:157], v[20:21], v[156:157]
	v_pk_mul_f32 v[158:159], v[22:23], v[158:159]
	v_lshlrev_b32_e32 v244, 16, v150
	v_and_b32_e32 v245, 0xffff0000, v150
	v_lshlrev_b32_e32 v246, 16, v151
	v_and_b32_e32 v247, 0xffff0000, v151
	v_pk_mul_f32 v[244:245], v[16:17], v[244:245]
	v_pk_mul_f32 v[246:247], v[18:19], v[246:247]
	v_cvt_pk_bf16_f32 v156, v156, v157
	v_cvt_pk_bf16_f32 v157, v158, v159
	v_cvt_pk_bf16_f32 v158, v244, v245
	v_cvt_pk_bf16_f32 v159, v246, v247
	v_add_u32_e32 v211, 0x90000, v163
	global_store_dwordx2 v211, v[156:157], s[6:7] offset:256
	global_store_dwordx2 v211, v[158:159], s[6:7] offset:288
	s_waitcnt vmcnt(21)
	v_lshlrev_b32_e32 v156, 16, v164
	v_and_b32_e32 v157, 0xffff0000, v164
	v_lshlrev_b32_e32 v158, 16, v165
	v_and_b32_e32 v159, 0xffff0000, v165
	v_pk_mul_f32 v[156:157], v[12:13], v[156:157]
	v_pk_mul_f32 v[158:159], v[14:15], v[158:159]
	v_lshlrev_b32_e32 v244, 16, v166
	v_and_b32_e32 v245, 0xffff0000, v166
	v_lshlrev_b32_e32 v246, 16, v167
	v_and_b32_e32 v247, 0xffff0000, v167
	v_pk_mul_f32 v[244:245], v[8:9], v[244:245]
	v_pk_mul_f32 v[246:247], v[10:11], v[246:247]
	v_cvt_pk_bf16_f32 v156, v156, v157
	v_cvt_pk_bf16_f32 v157, v158, v159
	v_cvt_pk_bf16_f32 v158, v244, v245
	v_cvt_pk_bf16_f32 v159, v246, v247
	v_add_u32_e32 v210, 0xa0000, v163
	global_store_dwordx2 v210, v[156:157], s[6:7] offset:256
	global_store_dwordx2 v210, v[158:159], s[6:7] offset:288
	s_waitcnt vmcnt(20)
	v_lshlrev_b32_e32 v156, 16, v172
	v_and_b32_e32 v157, 0xffff0000, v172
	v_lshlrev_b32_e32 v158, 16, v173
	v_and_b32_e32 v159, 0xffff0000, v173
	v_pk_mul_f32 v[156:157], v[4:5], v[156:157]
	v_pk_mul_f32 v[158:159], v[6:7], v[158:159]
	v_lshlrev_b32_e32 v244, 16, v174
	v_and_b32_e32 v245, 0xffff0000, v174
	v_lshlrev_b32_e32 v246, 16, v175
	v_and_b32_e32 v247, 0xffff0000, v175
	v_pk_mul_f32 v[244:245], v[0:1], v[244:245]
	v_pk_mul_f32 v[246:247], v[2:3], v[246:247]
	v_cvt_pk_bf16_f32 v156, v156, v157
	v_cvt_pk_bf16_f32 v157, v158, v159
	v_cvt_pk_bf16_f32 v158, v244, v245
	v_cvt_pk_bf16_f32 v159, v246, v247
	v_add_u32_e32 v211, 0xb0000, v163
	global_store_dwordx2 v211, v[156:157], s[6:7] offset:256
	global_store_dwordx2 v211, v[158:159], s[6:7] offset:288
	s_branch .LBB0_2313
